# P5 pass-3: next item's conv input rows prefetched during the current item's output stage (pass 1 already did this)
# speedup vs baseline: 1.0006x; 1.0006x over previous
.LBB0_794:
	s_mov_b32 s94, 0
	s_cmpk_gt_i32 s66, 0x3ff
	v_lshlrev_b32_e32 v160, 3, v0
	v_lshrrev_b32_e32 v133, 4, v1
	v_and_b32_e32 v130, 48, v1
	v_and_b32_e32 v159, 48, v0
	v_cmp_gt_u32_e64 s[4:5], 16, v1
	v_cmp_gt_u32_e64 s[6:7], 32, v1
	v_cmp_lt_u32_e64 s[8:9], 31, v1
	v_lshrrev_b32_e32 v158, 4, v0
	s_waitcnt vmcnt(0) lgkmcnt(0)
	s_barrier
	s_cbranch_scc1 .LBB0_819
	v_and_b32_e32 v6, 15, v0
	v_mov_b32_e32 v137, 0
	v_lshl_or_b32 v134, s97, 4, v6
	v_mov_b32_e32 v135, v137
	v_readlane_b32 s2, v250, 0
	v_lshlrev_b64 v[138:139], 8, v[134:135]
	v_readlane_b32 s3, v250, 1
	v_lshl_add_u64 v[2:3], s[74:75], 0, v[138:139]
	v_mov_b32_e32 v131, v137
	s_load_dwordx4 s[16:19], s[2:3], 0x80
	s_load_dwordx2 s[0:1], s[2:3], 0x98
	s_load_dwordx4 s[20:23], s[2:3], 0xa8
	v_lshl_add_u64 v[2:3], v[2:3], 0, v[130:131]
	s_mov_b64 s[2:3], 0xcc4000
	v_lshrrev_b32_e32 v5, 3, v0
	v_lshl_add_u64 v[140:141], v[2:3], 0, s[2:3]
	v_lshlrev_b32_e32 v2, 4, v6
	v_and_b32_e32 v161, 62, v5
	v_add_u32_e32 v3, 0, v2
	v_or_b32_e32 v5, 1, v5
	v_add_u32_e32 v2, v3, v2
	v_lshlrev_b32_e32 v8, 9, v161
	v_mul_u32_u24_e32 v9, 0x110, v5
	v_lshlrev_b32_e32 v5, 9, v5
	v_add_u32_e32 v165, v2, v8
	v_add_u32_e32 v167, v2, v5
	v_or_b32_e32 v22, 0x200, v0
	v_mbcnt_lo_u32_b32 v2, -1, 0
	v_and_b32_e32 v132, 0x78, v160
	v_lshlrev_b32_e32 v135, 11, v133
	v_lshrrev_b32_e32 v163, 4, v22
	v_mbcnt_hi_u32_b32 v2, -1, v2
	v_lshlrev_b32_e32 v4, 3, v133
	v_mul_u32_u24_e32 v7, 0x110, v161
	v_add_u32_e32 v10, 0, v159
	v_lshl_add_u32 v162, v134, 2, 0
	s_add_u32 s24, s74, 0xf9c4000
	v_mul_u32_u24_e32 v11, 0x110, v6
	v_or_b32_e32 v12, 0x4000, v135
	v_or_b32_e32 v13, 0x4200, v135
	v_or_b32_e32 v14, 0x4400, v135
	v_or_b32_e32 v15, 0x4600, v135
	v_or_b32_e32 v16, 0x6000, v135
	v_or_b32_e32 v17, 0x6200, v135
	v_or_b32_e32 v18, 0x6400, v135
	v_or_b32_e32 v19, 0x6600, v135
	v_lshl_add_u32 v20, v132, 2, 0
	v_lshlrev_b32_e32 v21, 9, v158
	v_lshlrev_b32_e32 v22, 9, v163
	v_and_or_b32 v2, v2, 64, v6
	v_lshlrev_b32_e32 v131, 3, v6
	s_mov_b32 s3, 0
	s_addc_u32 s25, s75, 0
	v_cmp_eq_u32_e64 s[10:11], 3, v133
	s_movk_i32 s33, 0x3000
	s_mov_b32 s42, 0x39c6000
	s_mov_b64 s[26:27], 0x1000
	s_movk_i32 s43, 0x1000
	s_mov_b64 s[28:29], 0x2000
	s_movk_i32 s44, 0x2000
	s_mov_b64 s[30:31], 0x3000
	v_add_u32_e32 v164, v3, v7
	v_add_u32_e32 v166, v3, v9
	v_add_u32_e32 v168, v10, v11
	v_lshlrev_b32_e32 v142, 1, v4
	s_mov_b64 s[34:35], 0xd04000
	s_mov_b32 s45, 0xd04000
	s_mov_b32 s46, 0xc1a00000
	s_mov_b32 s47, 0x3f2aaaab
	v_mov_b32_e32 v169, 0x3ecc95a3
	s_mov_b32 s48, 0x3f317218
	s_mov_b32 s49, 0x7f800000
	s_mov_b32 s50, 0x33800000
	v_add_u32_e32 v170, v162, v12
	v_add_u32_e32 v171, v162, v13
	v_add_u32_e32 v172, v162, v14
	v_add_u32_e32 v173, v162, v15
	v_add_u32_e32 v174, v162, v16
	v_add_u32_e32 v175, v162, v17
	v_add_u32_e32 v176, v162, v18
	v_add_u32_e32 v177, v162, v19
	v_add_u32_e32 v178, v20, v21
	v_add_u32_e32 v179, v20, v22
	v_mov_b32_e32 v144, 0x3f317218
	v_mov_b32_e32 v180, 0x7f800000
	v_mov_b32_e32 v181, 0x7fc00000
	v_mov_b32_e32 v182, 0xff800000
	v_lshlrev_b32_e32 v183, 2, v2
	s_mov_b32 s51, s66
	s_branch .LBB0_797
.LBB0_796:
	s_or_b64 exec, exec, s[12:13]
	s_waitcnt lgkmcnt(0)
	s_mov_b32 s94, 0
	s_add_i32 s76, s51, s70
	s_cmpk_gt_i32 s76, 0x3ff
	s_cbranch_scc1 .Lp5pf_none
	s_mov_b32 s94, 1
	s_ashr_i32 s77, s76, 3
	s_add_i32 s78, s77, 0x80
	s_lshl_b32 s78, s78, 6
	s_lshr_b32 s79, s77, 6
	s_lshl_b32 s79, s79, 12
	s_add_i32 s79, s79, 0x2000
	s_add_i32 s80, s79, 0x1000
	v_or_b32_e32 v86, s78, v161
	v_add_u32_e32 v86, -2, v86
	v_or_b32_e32 v92, s53, v132
	v_lshlrev_b32_e32 v92, 1, v92
	v_add_u32_e32 v92, 0x39c6000, v92
	v_mov_b32_e32 v93, 0
	v_mov_b32_e32 v89, s79
	v_add_u32_e32 v88, 0, v86
	v_cmp_le_i32_e32 vcc, s79, v88
	v_cmp_gt_i32_e64 s[82:83], s80, v88
	s_and_b64 s[84:85], vcc, s[82:83]
	v_mov_b32_e32 v90, s74
	v_mov_b32_e32 v91, s75
	v_cndmask_b32_e64 v88, v89, v88, s[84:85]
	v_mad_i64_i32 v[90:91], vcc, v88, s33, v[90:91]
	v_lshl_add_u64 v[90:91], v[90:91], 0, v[92:93]
	global_load_dwordx4 v[66:69], v[90:91], off
	v_add_u32_e32 v88, 1, v86
	v_cmp_le_i32_e32 vcc, s79, v88
	v_cmp_gt_i32_e64 s[82:83], s80, v88
	s_and_b64 s[86:87], vcc, s[82:83]
	v_mov_b32_e32 v90, s74
	v_mov_b32_e32 v91, s75
	v_cndmask_b32_e64 v88, v89, v88, s[86:87]
	v_mad_i64_i32 v[90:91], vcc, v88, s33, v[90:91]
	v_lshl_add_u64 v[90:91], v[90:91], 0, v[92:93]
	global_load_dwordx4 v[70:73], v[90:91], off
	v_add_u32_e32 v88, 2, v86
	v_cmp_le_i32_e32 vcc, s79, v88
	v_cmp_gt_i32_e64 s[82:83], s80, v88
	s_and_b64 s[88:89], vcc, s[82:83]
	v_mov_b32_e32 v90, s74
	v_mov_b32_e32 v91, s75
	v_cndmask_b32_e64 v88, v89, v88, s[88:89]
	v_mad_i64_i32 v[90:91], vcc, v88, s33, v[90:91]
	v_lshl_add_u64 v[90:91], v[90:91], 0, v[92:93]
	global_load_dwordx4 v[74:77], v[90:91], off
	v_add_u32_e32 v88, 3, v86
	v_cmp_le_i32_e32 vcc, s79, v88
	v_cmp_gt_i32_e64 s[82:83], s80, v88
	s_and_b64 s[90:91], vcc, s[82:83]
	v_mov_b32_e32 v90, s74
	v_mov_b32_e32 v91, s75
	v_cndmask_b32_e64 v88, v89, v88, s[90:91]
	v_mad_i64_i32 v[90:91], vcc, v88, s33, v[90:91]
	v_lshl_add_u64 v[90:91], v[90:91], 0, v[92:93]
	global_load_dwordx4 v[78:81], v[90:91], off
	v_add_u32_e32 v88, 4, v86
	v_cmp_le_i32_e32 vcc, s79, v88
	v_cmp_gt_i32_e64 s[82:83], s80, v88
	s_and_b64 s[92:93], vcc, s[82:83]
	v_mov_b32_e32 v90, s74
	v_mov_b32_e32 v91, s75
	v_cndmask_b32_e64 v88, v89, v88, s[92:93]
	v_mad_i64_i32 v[90:91], vcc, v88, s33, v[90:91]
	v_lshl_add_u64 v[90:91], v[90:91], 0, v[92:93]
	global_load_dwordx4 v[82:85], v[90:91], off
.Lp5pf_none:
	v_cndmask_b32_e64 v4, v11, 1.0, s[10:11]
	v_mul_f32_e32 v8, v4, v13
	v_cndmask_b32_e64 v4, v4, v8, s[6:7]
	v_mul_f32_e32 v8, v4, v9
	v_cndmask_b32_e64 v4, v4, v8, s[4:5]
	v_cndmask_b32_e64 v8, v62, 0, s[10:11]
	v_fmac_f32_e32 v63, v8, v13
	v_cndmask_b32_e64 v8, v8, v63, s[6:7]
	v_fmac_f32_e32 v10, v8, v9
	v_cndmask_b32_e64 v8, v8, v10, s[4:5]
	v_fmac_f32_e32 v8, v4, v64
	v_cndmask_b32_e64 v4, v204, 1.0, s[4:5]
	v_mul_f32_e32 v9, v4, v200
	v_cndmask_b32_e64 v4, v4, v9, s[8:9]
	v_mul_f32_e32 v9, v4, v198
	v_cndmask_b32_e64 v4, v4, v9, s[10:11]
	v_cndmask_b32_e64 v9, v202, 0, s[4:5]
	v_fmac_f32_e32 v201, v9, v200
	v_cndmask_b32_e64 v9, v9, v201, s[8:9]
	v_fmac_f32_e32 v199, v9, v198
	v_cndmask_b32_e64 v9, v9, v199, s[10:11]
	v_fmac_f32_e32 v9, v4, v230
	v_fmac_f32_e32 v196, v197, v9
	v_fmac_f32_e32 v5, v20, v8
	v_add_f32_e32 v4, 0, v196
	v_fmac_f32_e32 v194, v195, v9
	v_add_f32_e32 v4, v4, v5
	v_fmac_f32_e32 v2, v21, v8
	v_add_f32_e32 v5, 0, v194
	v_fmac_f32_e32 v192, v193, v9
	v_add_f32_e32 v2, v5, v2
	v_fmac_f32_e32 v6, v22, v8
	v_add_f32_e32 v5, 0, v192
	v_fmac_f32_e32 v191, v190, v9
	v_add_f32_e32 v5, v5, v6
	v_fmac_f32_e32 v7, v23, v8
	v_add_f32_e32 v6, 0, v191
	v_add_f32_e32 v6, v6, v7
	v_cndmask_b32_e64 v7, v60, 1.0, s[10:11]
	v_mul_f32_e32 v8, v7, v55
	v_cndmask_b32_e64 v7, v7, v8, s[6:7]
	v_mul_f32_e32 v8, v7, v56
	v_cndmask_b32_e64 v7, v7, v8, s[4:5]
	v_cndmask_b32_e64 v8, v59, 0, s[10:11]
	v_fmac_f32_e32 v58, v8, v55
	v_cndmask_b32_e64 v8, v8, v58, s[6:7]
	v_fmac_f32_e32 v57, v8, v56
	v_cndmask_b32_e64 v8, v8, v57, s[4:5]
	v_fmac_f32_e32 v8, v7, v61
	v_cndmask_b32_e64 v7, v229, 1.0, s[4:5]
	v_mul_f32_e32 v9, v7, v226
	v_cndmask_b32_e64 v7, v7, v9, s[8:9]
	v_mul_f32_e32 v9, v7, v224
	v_cndmask_b32_e64 v7, v7, v9, s[10:11]
	v_cndmask_b32_e64 v9, v228, 0, s[4:5]
	v_fmac_f32_e32 v227, v9, v226
	v_cndmask_b32_e64 v9, v9, v227, s[8:9]
	v_fmac_f32_e32 v225, v9, v224
	v_cndmask_b32_e64 v9, v9, v225, s[10:11]
	v_fmac_f32_e32 v9, v7, v189
	v_fmac_f32_e32 v222, v223, v9
	v_fmac_f32_e32 v220, v221, v9
	v_fmac_f32_e32 v212, v213, v9
	v_fmac_f32_e32 v185, v184, v9
	v_cndmask_b32_e64 v9, v53, 1.0, s[10:11]
	v_mul_f32_e32 v12, v9, v48
	v_cndmask_b32_e64 v9, v9, v12, s[6:7]
	v_mul_f32_e32 v12, v9, v49
	v_cndmask_b32_e64 v9, v9, v12, s[4:5]
	v_cndmask_b32_e64 v12, v52, 0, s[10:11]
	v_fmac_f32_e32 v51, v12, v48
	v_cndmask_b32_e64 v12, v12, v51, s[6:7]
	v_fmac_f32_e32 v50, v12, v49
	v_cndmask_b32_e64 v12, v12, v50, s[4:5]
	v_fmac_f32_e32 v12, v9, v54
	v_cndmask_b32_e64 v9, v219, 1.0, s[4:5]
	v_mul_f32_e32 v13, v9, v216
	v_cndmask_b32_e64 v9, v9, v13, s[8:9]
	v_mul_f32_e32 v13, v9, v214
	v_cndmask_b32_e64 v9, v9, v13, s[10:11]
	v_cndmask_b32_e64 v13, v218, 0, s[4:5]
	v_fmac_f32_e32 v217, v13, v216
	v_cndmask_b32_e64 v13, v13, v217, s[8:9]
	v_fmac_f32_e32 v215, v13, v214
	v_cndmask_b32_e64 v13, v13, v215, s[10:11]
	v_fmac_f32_e32 v13, v9, v207
	v_fmac_f32_e32 v210, v211, v13
	v_fmac_f32_e32 v208, v209, v13
	v_fmac_f32_e32 v205, v206, v13
	v_fmac_f32_e32 v187, v186, v13
	v_cndmask_b32_e64 v13, v41, 1.0, s[10:11]
	v_fmac_f32_e32 v17, v16, v12
	v_mul_f32_e32 v16, v13, v37
	v_cndmask_b32_e64 v13, v13, v16, s[6:7]
	v_mul_f32_e32 v16, v13, v30
	v_cndmask_b32_e64 v13, v13, v16, s[4:5]
	v_cndmask_b32_e64 v16, v40, 0, s[10:11]
	v_fmac_f32_e32 v39, v16, v37
	v_cndmask_b32_e64 v16, v16, v39, s[6:7]
	v_fmac_f32_e32 v38, v16, v30
	v_cndmask_b32_e64 v16, v16, v38, s[4:5]
	v_fmac_f32_e32 v16, v3, v13
	v_cndmask_b32_e64 v3, v109, 1.0, s[4:5]
	v_mul_f32_e32 v13, v3, v105
	v_cndmask_b32_e64 v3, v3, v13, s[8:9]
	v_mul_f32_e32 v13, v3, v107
	v_cndmask_b32_e64 v3, v3, v13, s[10:11]
	v_cndmask_b32_e64 v13, v129, 0, s[4:5]
	v_fmac_f32_e32 v128, v13, v105
	v_cndmask_b32_e64 v13, v13, v128, s[8:9]
	v_fmac_f32_e32 v104, v13, v107
	v_cndmask_b32_e64 v13, v13, v104, s[10:11]
	v_fmac_f32_e32 v13, v3, v203
	v_add_f32_e32 v9, 0, v210
	v_fmac_f32_e32 v102, v103, v13
	v_fmac_f32_e32 v15, v14, v8
	v_add_f32_e32 v7, 0, v222
	v_add_f32_e32 v9, v9, v17
	v_fmac_f32_e32 v34, v36, v12
	v_add_f32_e32 v14, 0, v208
	v_fmac_f32_e32 v124, v125, v13
	v_fmac_f32_e32 v27, v29, v16
	v_add_f32_e32 v17, 0, v102
	v_fmac_f32_e32 v100, v101, v13
	v_fmac_f32_e32 v99, v188, v13
	v_add_f32_e32 v7, v7, v15
	v_fmac_f32_e32 v45, v47, v8
	v_add_f32_e32 v10, 0, v220
	v_fmac_f32_e32 v43, v46, v8
	v_add_f32_e32 v11, 0, v212
	v_fmac_f32_e32 v42, v44, v8
	v_add_f32_e32 v8, 0, v185
	v_add_f32_e32 v14, v14, v34
	v_fmac_f32_e32 v32, v35, v12
	v_add_f32_e32 v15, 0, v205
	v_fmac_f32_e32 v31, v33, v12
	v_add_f32_e32 v12, 0, v187
	v_fmac_f32_e32 v19, v18, v16
	v_add_f32_e32 v3, 0, v124
	v_add_f32_e32 v17, v17, v27
	v_fmac_f32_e32 v25, v28, v16
	v_add_f32_e32 v18, 0, v100
	v_fmac_f32_e32 v24, v26, v16
	v_add_f32_e32 v13, 0, v99
	v_add_f32_e32 v10, v10, v45
	v_add_f32_e32 v11, v11, v43
	v_add_f32_e32 v8, v8, v42
	v_add_f32_e32 v15, v15, v32
	v_add_f32_e32 v12, v12, v31
	v_add_f32_e32 v3, v3, v19
	v_add_f32_e32 v18, v18, v25
	v_add_f32_e32 v13, v13, v24
	ds_write2st64_b32 v143, v6, v5 offset0:196 offset1:198
	ds_write2st64_b32 v143, v2, v4 offset0:200 offset1:202
	ds_write2st64_b32 v143, v8, v11 offset0:228 offset1:230
	ds_write2st64_b32 v143, v10, v7 offset0:232 offset1:234
	ds_write_b32 v170, v12 offset:50176
	ds_write_b32 v171, v15 offset:50176
	ds_write_b32 v172, v14 offset:50176
	ds_write_b32 v173, v9 offset:50176
	ds_write_b32 v174, v13 offset:50176
	ds_write_b32 v175, v18 offset:50176
	ds_write_b32 v176, v17 offset:50176
	ds_write_b32 v177, v3 offset:50176
	v_or_b32_e32 v14, s52, v158
	v_mov_b64_e32 v[16:17], s[74:75]
	s_lshl_b32 s2, s53, 1
	v_lshlrev_b32_e32 v136, 1, v132
	s_waitcnt lgkmcnt(0)
	s_barrier
	s_nop 0
	v_ashrrev_i32_e32 v15, 31, v14
	s_add_i32 s51, s51, s70
	s_cmpk_gt_i32 s51, 0x3ff
	v_mov_b32_e32 v2, v240
	v_mov_b32_e32 v3, v241
	v_mov_b32_e32 v4, v242
	v_mov_b32_e32 v5, v243
	v_lshlrev_b32_e32 v18, 16, v2
	v_and_b32_e32 v19, 0xffff0000, v2
	v_mul_f32_e32 v2, 0xbfb8aa3b, v18
	v_exp_f32_e32 v2, v2
	v_mul_f32_e32 v6, 0xbfb8aa3b, v19
	v_exp_f32_e32 v6, v6
	v_add_f32_e32 v2, 1.0, v2
	v_rcp_f32_e32 v20, v2
	v_add_f32_e32 v2, 1.0, v6
	v_rcp_f32_e32 v21, v2
	ds_read_b128 v[6:9], v178 offset:50176
	ds_read_b128 v[10:13], v178 offset:50192
	v_pk_mul_f32 v[18:19], v[20:21], v[18:19]
	v_lshlrev_b32_e32 v20, 16, v4
	v_and_b32_e32 v21, 0xffff0000, v4
	v_mul_f32_e32 v2, 0xbfb8aa3b, v20
	v_exp_f32_e32 v2, v2
	v_mul_f32_e32 v4, 0xbfb8aa3b, v21
	v_exp_f32_e32 v4, v4
	s_waitcnt lgkmcnt(1)
	v_pk_mul_f32 v[6:7], v[6:7], v[18:19]
	v_add_f32_e32 v2, 1.0, v2
	v_rcp_f32_e32 v18, v2
	v_add_f32_e32 v2, 1.0, v4
	v_rcp_f32_e32 v19, v2
	v_lshlrev_b32_e32 v2, 16, v3
	v_and_b32_e32 v3, 0xffff0000, v3
	v_mul_f32_e32 v4, 0xbfb8aa3b, v2
	v_pk_mul_f32 v[18:19], v[18:19], v[20:21]
	v_lshlrev_b32_e32 v20, 16, v5
	v_mul_f32_e32 v22, 0xbfb8aa3b, v3
	v_and_b32_e32 v21, 0xffff0000, v5
	v_mul_f32_e32 v5, 0xbfb8aa3b, v20
	v_exp_f32_e32 v4, v4
	v_exp_f32_e32 v22, v22
	v_exp_f32_e32 v23, v5
	v_mul_f32_e32 v5, 0xbfb8aa3b, v21
	v_exp_f32_e32 v24, v5
	v_add_f32_e32 v4, 1.0, v4
	v_add_f32_e32 v22, 1.0, v22
	v_rcp_f32_e32 v4, v4
	v_rcp_f32_e32 v5, v22
	v_add_f32_e32 v22, 1.0, v23
	v_add_f32_e32 v23, 1.0, v24
	v_rcp_f32_e32 v22, v22
	v_rcp_f32_e32 v23, v23
	v_pk_mul_f32 v[2:3], v[4:5], v[2:3]
	s_waitcnt lgkmcnt(0)
	v_pk_mul_f32 v[10:11], v[10:11], v[18:19]
	v_pk_mul_f32 v[4:5], v[8:9], v[2:3]
	v_pk_mul_f32 v[2:3], v[22:23], v[20:21]
	s_nop 0
	v_pk_mul_f32 v[8:9], v[12:13], v[2:3]
	v_cvt_pk_bf16_f32 v2, v6, v7
	v_lshlrev_b64 v[6:7], 12, v[14:15]
	v_lshl_add_u64 v[6:7], s[72:73], 0, v[6:7]
	v_lshl_add_u64 v[6:7], v[6:7], 0, s[2:3]
	v_cvt_pk_bf16_f32 v3, v4, v5
	v_cvt_pk_bf16_f32 v4, v10, v11
	v_cvt_pk_bf16_f32 v5, v8, v9
	v_lshl_add_u64 v[6:7], v[6:7], 0, v[136:137]
	v_add_u32_e32 v14, s52, v163
	global_store_dwordx4 v[6:7], v[2:5], off offset:2048
	v_ashrrev_i32_e32 v15, 31, v14
	s_nop 0
	s_nop 0
	v_mov_b32_e32 v2, v244
	v_mov_b32_e32 v3, v245
	v_mov_b32_e32 v4, v246
	v_mov_b32_e32 v5, v247
	v_lshlrev_b32_e32 v16, 16, v2
	v_and_b32_e32 v17, 0xffff0000, v2
	v_mul_f32_e32 v2, 0xbfb8aa3b, v16
	v_exp_f32_e32 v2, v2
	v_mul_f32_e32 v6, 0xbfb8aa3b, v17
	v_exp_f32_e32 v6, v6
	v_add_f32_e32 v2, 1.0, v2
	v_rcp_f32_e32 v18, v2
	v_add_f32_e32 v2, 1.0, v6
	v_rcp_f32_e32 v19, v2
	ds_read_b128 v[6:9], v179 offset:50176
	ds_read_b128 v[10:13], v179 offset:50192
	v_pk_mul_f32 v[16:17], v[18:19], v[16:17]
	v_lshlrev_b32_e32 v18, 16, v4
	v_and_b32_e32 v19, 0xffff0000, v4
	v_mul_f32_e32 v2, 0xbfb8aa3b, v18
	v_exp_f32_e32 v2, v2
	v_mul_f32_e32 v4, 0xbfb8aa3b, v19
	v_exp_f32_e32 v4, v4
	s_waitcnt lgkmcnt(1)
	v_pk_mul_f32 v[6:7], v[6:7], v[16:17]
	v_add_f32_e32 v2, 1.0, v2
	v_rcp_f32_e32 v16, v2
	v_add_f32_e32 v2, 1.0, v4
	v_rcp_f32_e32 v17, v2
	v_lshlrev_b32_e32 v2, 16, v3
	v_and_b32_e32 v3, 0xffff0000, v3
	v_mul_f32_e32 v4, 0xbfb8aa3b, v2
	v_pk_mul_f32 v[16:17], v[16:17], v[18:19]
	v_lshlrev_b32_e32 v18, 16, v5
	v_mul_f32_e32 v20, 0xbfb8aa3b, v3
	v_and_b32_e32 v19, 0xffff0000, v5
	v_mul_f32_e32 v5, 0xbfb8aa3b, v18
	v_exp_f32_e32 v4, v4
	v_exp_f32_e32 v20, v20
	v_exp_f32_e32 v21, v5
	v_mul_f32_e32 v5, 0xbfb8aa3b, v19
	v_exp_f32_e32 v22, v5
	v_add_f32_e32 v4, 1.0, v4
	v_add_f32_e32 v20, 1.0, v20
	v_rcp_f32_e32 v4, v4
	v_rcp_f32_e32 v5, v20
	v_add_f32_e32 v20, 1.0, v21
	v_add_f32_e32 v21, 1.0, v22
	v_rcp_f32_e32 v20, v20
	v_rcp_f32_e32 v21, v21
	v_pk_mul_f32 v[2:3], v[4:5], v[2:3]
	s_waitcnt lgkmcnt(0)
	v_pk_mul_f32 v[10:11], v[10:11], v[16:17]
	v_pk_mul_f32 v[4:5], v[8:9], v[2:3]
	v_pk_mul_f32 v[2:3], v[20:21], v[18:19]
	s_nop 0
	v_pk_mul_f32 v[8:9], v[12:13], v[2:3]
	v_cvt_pk_bf16_f32 v2, v6, v7
	v_lshlrev_b64 v[6:7], 12, v[14:15]
	v_lshl_add_u64 v[6:7], s[72:73], 0, v[6:7]
	v_lshl_add_u64 v[6:7], v[6:7], 0, s[2:3]
	v_cvt_pk_bf16_f32 v3, v4, v5
	v_cvt_pk_bf16_f32 v4, v10, v11
	v_cvt_pk_bf16_f32 v5, v8, v9
	v_lshl_add_u64 v[6:7], v[6:7], 0, v[136:137]
	global_store_dwordx4 v[6:7], v[2:5], off offset:2048
	s_waitcnt lgkmcnt(0)
	s_barrier
	s_cbranch_scc1 .LBB0_819
.LBB0_797:
	s_ashr_i32 s39, s51, 3
	s_add_i32 s54, s39, 0x80
	s_and_b32 s2, s51, 7
	s_lshl_b32 s53, s2, 7
	s_lshl_b32 s52, s54, 6
	s_cmp_gt_i32 s39, -1
	s_cselect_b64 s[14:15], -1, 0
	s_and_b32 s38, s54, -4
	s_and_b32 s12, s54, 0x7fffffc0
	s_add_i32 s40, s38, 4
	s_add_i32 s13, s12, 64
	s_cmp_lt_i32 s39, 0
	s_cselect_b32 s13, s40, s13
	s_cselect_b32 s12, s38, s12
	v_or_b32_e32 v15, s52, v161
	v_add_u32_e32 v6, -2, v15
	s_lshl_b32 s36, s12, 6
	v_or_b32_e32 v251, s52, v158
	v_mov_b32_e32 v248, s74
	v_mov_b32_e32 v249, s75
	v_add_u32_e32 v240, s53, v132
	v_lshlrev_b32_e32 v240, 1, v240
	v_add_u32_e32 v240, s42, v240
	v_mov_b32_e32 v241, 0
	v_mad_i64_i32 v[248:249], vcc, v251, s33, v[248:249]
	v_lshl_add_u64 v[248:249], v[248:249], 0, v[240:241]
	global_load_dwordx4 v[240:243], v[248:249], off offset:2048
	v_add_u32_e32 v251, s52, v163
	v_mov_b32_e32 v246, s74
	v_mov_b32_e32 v247, s75
	v_add_u32_e32 v244, s53, v132
	v_lshlrev_b32_e32 v244, 1, v244
	v_add_u32_e32 v244, s42, v244
	v_mov_b32_e32 v245, 0
	v_mad_i64_i32 v[246:247], vcc, v251, s33, v[246:247]
	v_lshl_add_u64 v[246:247], v[246:247], 0, v[244:245]
	global_load_dwordx4 v[244:247], v[246:247], off offset:2048
	s_lshl_b32 s37, s13, 6
	s_cmp_eq_u32 s94, 0
	s_cbranch_scc1 .Lp5pf_orig
	s_waitcnt vmcnt(4)
	v_cndmask_b32_e64 v2, 0, v66, s[84:85]
	v_cndmask_b32_e64 v3, 0, v67, s[84:85]
	v_cndmask_b32_e64 v4, 0, v68, s[84:85]
	v_cndmask_b32_e64 v5, 0, v69, s[84:85]
	v_cndmask_b32_e64 v10, 0, v70, s[86:87]
	v_cndmask_b32_e64 v11, 0, v71, s[86:87]
	v_cndmask_b32_e64 v12, 0, v72, s[86:87]
	v_cndmask_b32_e64 v13, 0, v73, s[86:87]
	v_cndmask_b32_e64 v6, 0, v74, s[88:89]
	v_cndmask_b32_e64 v7, 0, v75, s[88:89]
	v_cndmask_b32_e64 v8, 0, v76, s[88:89]
	v_cndmask_b32_e64 v9, 0, v77, s[88:89]
	v_cndmask_b32_e64 v18, 0, v78, s[90:91]
	v_cndmask_b32_e64 v19, 0, v79, s[90:91]
	v_cndmask_b32_e64 v20, 0, v80, s[90:91]
	v_cndmask_b32_e64 v21, 0, v81, s[90:91]
	v_cndmask_b32_e64 v14, 0, v82, s[92:93]
	v_cndmask_b32_e64 v15, 0, v83, s[92:93]
	v_cndmask_b32_e64 v16, 0, v84, s[92:93]
	v_cndmask_b32_e64 v17, 0, v85, s[92:93]
	s_branch .LBB0_807
.Lp5pf_orig:
	v_or_b32_e32 v2, s53, v132
	v_cmp_le_i32_e32 vcc, s36, v6
	v_cmp_gt_i32_e64 s[12:13], s37, v6
	s_and_b64 s[56:57], vcc, s[12:13]
	v_lshlrev_b32_e32 v136, 1, v2
	v_mov_b32_e32 v2, 0
	v_mov_b32_e32 v3, 0
	v_mov_b32_e32 v4, 0
	v_mov_b32_e32 v5, 0
	s_and_saveexec_b64 s[12:13], s[56:57]
	s_cbranch_execz .LBB0_799
	v_mov_b64_e32 v[2:3], s[74:75]
	v_mad_i64_i32 v[2:3], s[56:57], v6, s33, v[2:3]
	v_lshl_add_u64 v[2:3], v[2:3], 0, v[136:137]
	v_add_co_u32_e32 v2, vcc, 0x39c6000, v2
	s_nop 1
	v_addc_co_u32_e32 v3, vcc, 0, v3, vcc
	global_load_dwordx4 v[2:5], v[2:3], off
